# EP_RES epilogue: batched base loads (12 in flight per wave) instead of 32 serialized load-wait-store round trips
# speedup vs baseline: 1.0290x; 1.0290x over previous
; __device__ __forceinline__ unsigned cvt_pk_bf16(float lo, float hi) { f32x2 v = {lo, hi}; bf16x2_t b = __builtin_convertvector(v, bf16x2_t); return __builtin_bit_cast(unsigned, b); }
; template <int MODE> __device__ __forceinline__ void gemm_epilogue(f32x4 (&acc)[2][2][4][2], const GD& g, const pg8::Unit& u, int wr, int wc, int fr, int fq, LAS unsigned char* lds, const float (&rsv)[2][4]) {
;     ...
;     } else if constexpr (MODE == EP_RES) {
;         const float* base = g.f0; float* out = (float*)g.o0; bf16_t* xb = (bf16_t*)g.o1; float* ssq = (float*)g.f1;
;         const int col0 = u.pn * 256 + wc * 32 + 4 * fq; const int rz = (u.z / g.nz2) * g.ro1;
; #pragma unroll
;         for (int ai = 0; ai < 2; ++ai)
; #pragma unroll
;             for (int m = 0; m < 4; ++m) { const size_t off = (size_t)(rz + rt + ai * 128 + m * 16) * DM + col0;
;                 float ss = 0.f;
; #pragma unroll
;                 for (int bj = 0; bj < 2; ++bj)
; #pragma unroll
;                     for (int n = 0; n < 2; ++n) { const f32x4 bs = *(const f32x4*)(base + off + bj * 128 + n * 16); const f32x4 y = bs + acc[ai][bj][m][n]; *(f32x4*)(out + off + bj * 128 + n * 16) = y;
;                         ss += (y[0] * y[0] + y[1] * y[1]) + (y[2] * y[2] + y[3] * y[3]);
;                         u32x2 w; w.x = cvt_pk_bf16(y[0], y[1]); w.y = cvt_pk_bf16(y[2], y[3]); if (xb) *(u32x2*)(xb + off + bj * 128 + n * 16) = w; }
;                 ss += __shfl_xor(ss, 16); ss += __shfl_xor(ss, 32);
;                 if (fq == 0) __hip_atomic_fetch_add(ssq + rz + rt + ai * 128 + m * 16, ss, __ATOMIC_RELAXED, __HIP_MEMORY_SCOPE_AGENT); }
.LBB0_196:
	s_abs_i32 s3, s38
	s_mul_hi_u32 s8, s3, s0
	s_mul_i32 s9, s8, s1
	s_ashr_i32 s2, s38, 31
	s_sub_i32 s3, s3, s9
	s_xor_b32 s2, s2, s52
	s_add_i32 s9, s8, 1
	s_sub_i32 s12, s3, s1
	s_cmp_ge_u32 s3, s1
	s_cselect_b32 s8, s9, s8
	s_cselect_b32 s3, s12, s3
	s_add_i32 s9, s8, 1
	s_cmp_ge_u32 s3, s1
	s_cselect_b32 s3, s9, s8
	s_xor_b32 s3, s3, s2
	s_sub_i32 s2, s3, s2
	v_readlane_b32 s3, v254, 59
	v_readlane_b32 s8, v254, 42
	v_lshl_add_u32 v144, s56, 8, v154
	s_mul_i32 s2, s2, s3
	v_readlane_b32 s9, v254, 43
	v_add_u32_e32 v144, s2, v144
	v_lshl_or_b32 v145, s53, 8, v164
	v_readlane_b32 s2, v254, 48
	v_readlane_b32 s3, v254, 49
	v_lshlrev_b32_e32 v146, 2, v144
	v_lshl_add_u32 v143, v144, 11, v145
	v_and_b32_e32 v149, 64, v252
	v_lshlrev_b32_e32 v147, 1, v143
	v_lshlrev_b32_e32 v143, 2, v143
	v_xor_b32_e32 v1, 16, v252
	v_add_u32_e32 v149, 64, v149
	v_xor_b32_e32 v142, 32, v252
	v_mov_b32_e32 v148, v143
	v_cmp_lt_i32_e32 vcc, v1, v149
	s_nop 1
	v_cndmask_b32_e32 v1, v252, v1, vcc
	v_cmp_lt_i32_e32 vcc, v142, v149
	v_lshlrev_b32_e32 v1, 2, v1
	s_nop 0
	v_cndmask_b32_e32 v142, v252, v142, vcc
	v_lshlrev_b32_e32 v142, 2, v142
	s_and_b64 vcc, exec, s[62:63]
	s_cbranch_vccz .Lres_noxb
	global_load_dwordx4 v[168:171], v143, s[2:3] offset:0
	global_load_dwordx4 v[172:175], v143, s[2:3] offset:64
	global_load_dwordx4 v[176:179], v143, s[2:3] offset:512
	global_load_dwordx4 v[180:183], v143, s[2:3] offset:576
	v_add_u32_e32 v143, 0x20000, v143
	global_load_dwordx4 v[184:187], v143, s[2:3] offset:0
	global_load_dwordx4 v[188:191], v143, s[2:3] offset:64
	global_load_dwordx4 v[196:199], v143, s[2:3] offset:512
	global_load_dwordx4 v[204:207], v143, s[2:3] offset:576
	v_add_u32_e32 v143, 0x20000, v143
	global_load_dwordx4 v[220:223], v143, s[2:3] offset:0
	global_load_dwordx4 v[224:227], v143, s[2:3] offset:64
	global_load_dwordx4 v[228:231], v143, s[2:3] offset:512
	global_load_dwordx4 v[232:235], v143, s[2:3] offset:576
	s_waitcnt vmcnt(8)
	v_pk_add_f32 v[128:129], v[128:129], v[170:171]
	v_pk_add_f32 v[126:127], v[126:127], v[168:169]
	v_pk_add_f32 v[124:125], v[124:125], v[174:175]
	v_pk_add_f32 v[122:123], v[122:123], v[172:173]
	v_pk_add_f32 v[120:121], v[120:121], v[178:179]
	v_pk_add_f32 v[118:119], v[118:119], v[176:177]
	v_pk_add_f32 v[116:117], v[116:117], v[182:183]
	v_pk_add_f32 v[114:115], v[114:115], v[180:181]
	global_store_dwordx4 v148, v[126:129], s[8:9] offset:0
	global_store_dwordx4 v148, v[122:125], s[8:9] offset:64
	global_store_dwordx4 v148, v[118:121], s[8:9] offset:512
	global_store_dwordx4 v148, v[114:117], s[8:9] offset:576
	v_cvt_pk_bf16_f32 v168, v126, v127
	v_cvt_pk_bf16_f32 v169, v128, v129
	v_cvt_pk_bf16_f32 v172, v122, v123
	v_cvt_pk_bf16_f32 v173, v124, v125
	v_cvt_pk_bf16_f32 v176, v118, v119
	v_cvt_pk_bf16_f32 v177, v120, v121
	v_cvt_pk_bf16_f32 v180, v114, v115
	v_cvt_pk_bf16_f32 v181, v116, v117
	global_store_dwordx2 v147, v[168:169], s[36:37] offset:0
	global_store_dwordx2 v147, v[172:173], s[36:37] offset:32
	global_store_dwordx2 v147, v[176:177], s[36:37] offset:256
	global_store_dwordx2 v147, v[180:181], s[36:37] offset:288
	v_mul_f32_e32 v150, v127, v127
	v_mul_f32_e32 v151, v129, v129
	v_fmac_f32_e32 v150, v126, v126
	v_fmac_f32_e32 v151, v128, v128
	v_add_f32_e32 v150, v150, v151
	v_mul_f32_e32 v152, v123, v123
	v_mul_f32_e32 v153, v125, v125
	v_fmac_f32_e32 v152, v122, v122
	v_fmac_f32_e32 v153, v124, v124
	v_add_f32_e32 v152, v152, v153
	v_add_f32_e32 v150, v150, v152
	v_mul_f32_e32 v152, v119, v119
	v_mul_f32_e32 v153, v121, v121
	v_fmac_f32_e32 v152, v118, v118
	v_fmac_f32_e32 v153, v120, v120
	v_add_f32_e32 v152, v152, v153
	v_add_f32_e32 v150, v150, v152
	v_mul_f32_e32 v152, v115, v115
	v_mul_f32_e32 v153, v117, v117
	v_fmac_f32_e32 v152, v114, v114
	v_fmac_f32_e32 v153, v116, v116
	v_add_f32_e32 v152, v152, v153
	v_add_f32_e32 v150, v150, v152
	ds_bpermute_b32 v192, v1, v150
	v_add_u32_e32 v143, 0x20000, v143
	global_load_dwordx4 v[168:171], v143, s[2:3] offset:0
	global_load_dwordx4 v[172:175], v143, s[2:3] offset:64
	global_load_dwordx4 v[176:179], v143, s[2:3] offset:512
	global_load_dwordx4 v[180:183], v143, s[2:3] offset:576
	s_waitcnt lgkmcnt(0)
	v_add_f32_e32 v150, v150, v192
	ds_bpermute_b32 v192, v142, v150
	v_add_u32_e32 v148, 0x20000, v148
	v_add_u32_e32 v147, 0x10000, v147
	s_and_saveexec_b64 s[12:13], s[6:7]
	s_waitcnt lgkmcnt(0)
	v_add_f32_e32 v150, v150, v192
	global_atomic_add_f32 v146, v150, s[70:71] offset:0
	s_mov_b64 exec, s[12:13]
	s_waitcnt vmcnt(17)
	v_pk_add_f32 v[112:113], v[112:113], v[186:187]
	v_pk_add_f32 v[110:111], v[110:111], v[184:185]
	v_pk_add_f32 v[108:109], v[108:109], v[190:191]
	v_pk_add_f32 v[106:107], v[106:107], v[188:189]
	v_pk_add_f32 v[104:105], v[104:105], v[198:199]
	v_pk_add_f32 v[102:103], v[102:103], v[196:197]
	v_pk_add_f32 v[100:101], v[100:101], v[206:207]
	v_pk_add_f32 v[98:99], v[98:99], v[204:205]
	global_store_dwordx4 v148, v[110:113], s[8:9] offset:0
	global_store_dwordx4 v148, v[106:109], s[8:9] offset:64
	global_store_dwordx4 v148, v[102:105], s[8:9] offset:512
	global_store_dwordx4 v148, v[98:101], s[8:9] offset:576
	v_cvt_pk_bf16_f32 v184, v110, v111
	v_cvt_pk_bf16_f32 v185, v112, v113
	v_cvt_pk_bf16_f32 v188, v106, v107
	v_cvt_pk_bf16_f32 v189, v108, v109
	v_cvt_pk_bf16_f32 v196, v102, v103
	v_cvt_pk_bf16_f32 v197, v104, v105
	v_cvt_pk_bf16_f32 v204, v98, v99
	v_cvt_pk_bf16_f32 v205, v100, v101
	global_store_dwordx2 v147, v[184:185], s[36:37] offset:0
	global_store_dwordx2 v147, v[188:189], s[36:37] offset:32
	global_store_dwordx2 v147, v[196:197], s[36:37] offset:256
	global_store_dwordx2 v147, v[204:205], s[36:37] offset:288
	v_mul_f32_e32 v150, v111, v111
	v_mul_f32_e32 v151, v113, v113
	v_fmac_f32_e32 v150, v110, v110
	v_fmac_f32_e32 v151, v112, v112
	v_add_f32_e32 v150, v150, v151
	v_mul_f32_e32 v152, v107, v107
	v_mul_f32_e32 v153, v109, v109
	v_fmac_f32_e32 v152, v106, v106
	v_fmac_f32_e32 v153, v108, v108
	v_add_f32_e32 v152, v152, v153
	v_add_f32_e32 v150, v150, v152
	v_mul_f32_e32 v152, v103, v103
	v_mul_f32_e32 v153, v105, v105
	v_fmac_f32_e32 v152, v102, v102
	v_fmac_f32_e32 v153, v104, v104
	v_add_f32_e32 v152, v152, v153
	v_add_f32_e32 v150, v150, v152
	v_mul_f32_e32 v152, v99, v99
	v_mul_f32_e32 v153, v101, v101
	v_fmac_f32_e32 v152, v98, v98
	v_fmac_f32_e32 v153, v100, v100
	v_add_f32_e32 v152, v152, v153
	v_add_f32_e32 v150, v150, v152
	ds_bpermute_b32 v192, v1, v150
	v_add_u32_e32 v143, 0xa0000, v143
	global_load_dwordx4 v[184:187], v143, s[2:3] offset:0
	global_load_dwordx4 v[188:191], v143, s[2:3] offset:64
	global_load_dwordx4 v[196:199], v143, s[2:3] offset:512
	global_load_dwordx4 v[204:207], v143, s[2:3] offset:576
	s_waitcnt lgkmcnt(0)
; __device__ __forceinline__ unsigned cvt_pk_bf16(float lo, float hi) { f32x2 v = {lo, hi}; bf16x2_t b = __builtin_convertvector(v, bf16x2_t); return __builtin_bit_cast(unsigned, b); }
; template <int MODE> __device__ __forceinline__ void gemm_epilogue(f32x4 (&acc)[2][2][4][2], const GD& g, const pg8::Unit& u, int wr, int wc, int fr, int fq, LAS unsigned char* lds, const float (&rsv)[2][4]) {
;     ...
; #pragma unroll
;         for (int ai = 0; ai < 2; ++ai)
; #pragma unroll
;             for (int m = 0; m < 4; ++m) { const size_t off = (size_t)(rz + rt + ai * 128 + m * 16) * DM + col0;
;                 float ss = 0.f;
; #pragma unroll
;                 for (int bj = 0; bj < 2; ++bj)
; #pragma unroll
;                     for (int n = 0; n < 2; ++n) { const f32x4 bs = *(const f32x4*)(base + off + bj * 128 + n * 16); const f32x4 y = bs + acc[ai][bj][m][n]; *(f32x4*)(out + off + bj * 128 + n * 16) = y;
;                         ss += (y[0] * y[0] + y[1] * y[1]) + (y[2] * y[2] + y[3] * y[3]);
;                         u32x2 w; w.x = cvt_pk_bf16(y[0], y[1]); w.y = cvt_pk_bf16(y[2], y[3]); if (xb) *(u32x2*)(xb + off + bj * 128 + n * 16) = w; }
;                 ss += __shfl_xor(ss, 16); ss += __shfl_xor(ss, 32);
;                 if (fq == 0) __hip_atomic_fetch_add(ssq + rz + rt + ai * 128 + m * 16, ss, __ATOMIC_RELAXED, __HIP_MEMORY_SCOPE_AGENT); }
	v_add_f32_e32 v150, v150, v192
	ds_bpermute_b32 v192, v142, v150
	v_add_u32_e32 v148, 0x20000, v148
	v_add_u32_e32 v147, 0x10000, v147
	s_and_saveexec_b64 s[12:13], s[6:7]
	s_waitcnt lgkmcnt(0)
	v_add_f32_e32 v150, v150, v192
	global_atomic_add_f32 v146, v150, s[70:71] offset:64
	s_mov_b64 exec, s[12:13]
	s_waitcnt vmcnt(26)
	v_pk_add_f32 v[96:97], v[96:97], v[222:223]
	v_pk_add_f32 v[94:95], v[94:95], v[220:221]
	v_pk_add_f32 v[92:93], v[92:93], v[226:227]
	v_pk_add_f32 v[90:91], v[90:91], v[224:225]
	v_pk_add_f32 v[88:89], v[88:89], v[230:231]
	v_pk_add_f32 v[86:87], v[86:87], v[228:229]
	v_pk_add_f32 v[84:85], v[84:85], v[234:235]
	v_pk_add_f32 v[82:83], v[82:83], v[232:233]
	global_store_dwordx4 v148, v[94:97], s[8:9] offset:0
	global_store_dwordx4 v148, v[90:93], s[8:9] offset:64
	global_store_dwordx4 v148, v[86:89], s[8:9] offset:512
	global_store_dwordx4 v148, v[82:85], s[8:9] offset:576
	v_cvt_pk_bf16_f32 v220, v94, v95
	v_cvt_pk_bf16_f32 v221, v96, v97
	v_cvt_pk_bf16_f32 v224, v90, v91
	v_cvt_pk_bf16_f32 v225, v92, v93
	v_cvt_pk_bf16_f32 v228, v86, v87
	v_cvt_pk_bf16_f32 v229, v88, v89
	v_cvt_pk_bf16_f32 v232, v82, v83
	v_cvt_pk_bf16_f32 v233, v84, v85
	global_store_dwordx2 v147, v[220:221], s[36:37] offset:0
	global_store_dwordx2 v147, v[224:225], s[36:37] offset:32
	global_store_dwordx2 v147, v[228:229], s[36:37] offset:256
	global_store_dwordx2 v147, v[232:233], s[36:37] offset:288
	v_mul_f32_e32 v150, v95, v95
	v_mul_f32_e32 v151, v97, v97
	v_fmac_f32_e32 v150, v94, v94
	v_fmac_f32_e32 v151, v96, v96
	v_add_f32_e32 v150, v150, v151
	v_mul_f32_e32 v152, v91, v91
	v_mul_f32_e32 v153, v93, v93
	v_fmac_f32_e32 v152, v90, v90
	v_fmac_f32_e32 v153, v92, v92
	v_add_f32_e32 v152, v152, v153
	v_add_f32_e32 v150, v150, v152
	v_mul_f32_e32 v152, v87, v87
	v_mul_f32_e32 v153, v89, v89
	v_fmac_f32_e32 v152, v86, v86
	v_fmac_f32_e32 v153, v88, v88
	v_add_f32_e32 v152, v152, v153
	v_add_f32_e32 v150, v150, v152
	v_mul_f32_e32 v152, v83, v83
	v_mul_f32_e32 v153, v85, v85
	v_fmac_f32_e32 v152, v82, v82
	v_fmac_f32_e32 v153, v84, v84
	v_add_f32_e32 v152, v152, v153
	v_add_f32_e32 v150, v150, v152
	ds_bpermute_b32 v192, v1, v150
	v_add_u32_e32 v143, 0x20000, v143
	global_load_dwordx4 v[220:223], v143, s[2:3] offset:0
	global_load_dwordx4 v[224:227], v143, s[2:3] offset:64
	global_load_dwordx4 v[228:231], v143, s[2:3] offset:512
	global_load_dwordx4 v[232:235], v143, s[2:3] offset:576
	s_waitcnt lgkmcnt(0)
	v_add_f32_e32 v150, v150, v192
	ds_bpermute_b32 v192, v142, v150
	v_add_u32_e32 v148, 0x20000, v148
	v_add_u32_e32 v147, 0x10000, v147
	s_and_saveexec_b64 s[12:13], s[6:7]
	s_waitcnt lgkmcnt(0)
	v_add_f32_e32 v150, v150, v192
	global_atomic_add_f32 v146, v150, s[70:71] offset:128
	s_mov_b64 exec, s[12:13]
	s_waitcnt vmcnt(27)
	v_pk_add_f32 v[80:81], v[80:81], v[170:171]
	v_pk_add_f32 v[78:79], v[78:79], v[168:169]
	v_pk_add_f32 v[76:77], v[76:77], v[174:175]
	v_pk_add_f32 v[74:75], v[74:75], v[172:173]
	v_pk_add_f32 v[72:73], v[72:73], v[178:179]
	v_pk_add_f32 v[70:71], v[70:71], v[176:177]
	v_pk_add_f32 v[68:69], v[68:69], v[182:183]
	v_pk_add_f32 v[66:67], v[66:67], v[180:181]
	global_store_dwordx4 v148, v[78:81], s[8:9] offset:0
	global_store_dwordx4 v148, v[74:77], s[8:9] offset:64
	global_store_dwordx4 v148, v[70:73], s[8:9] offset:512
	global_store_dwordx4 v148, v[66:69], s[8:9] offset:576
	v_cvt_pk_bf16_f32 v168, v78, v79
	v_cvt_pk_bf16_f32 v169, v80, v81
	v_cvt_pk_bf16_f32 v172, v74, v75
	v_cvt_pk_bf16_f32 v173, v76, v77
	v_cvt_pk_bf16_f32 v176, v70, v71
	v_cvt_pk_bf16_f32 v177, v72, v73
	v_cvt_pk_bf16_f32 v180, v66, v67
	v_cvt_pk_bf16_f32 v181, v68, v69
	global_store_dwordx2 v147, v[168:169], s[36:37] offset:0
	global_store_dwordx2 v147, v[172:173], s[36:37] offset:32
	global_store_dwordx2 v147, v[176:177], s[36:37] offset:256
	global_store_dwordx2 v147, v[180:181], s[36:37] offset:288
	v_mul_f32_e32 v150, v79, v79
	v_mul_f32_e32 v151, v81, v81
	v_fmac_f32_e32 v150, v78, v78
	v_fmac_f32_e32 v151, v80, v80
	v_add_f32_e32 v150, v150, v151
	v_mul_f32_e32 v152, v75, v75
	v_mul_f32_e32 v153, v77, v77
	v_fmac_f32_e32 v152, v74, v74
	v_fmac_f32_e32 v153, v76, v76
	v_add_f32_e32 v152, v152, v153
	v_add_f32_e32 v150, v150, v152
	v_mul_f32_e32 v152, v71, v71
	v_mul_f32_e32 v153, v73, v73
	v_fmac_f32_e32 v152, v70, v70
	v_fmac_f32_e32 v153, v72, v72
	v_add_f32_e32 v152, v152, v153
	v_add_f32_e32 v150, v150, v152
	v_mul_f32_e32 v152, v67, v67
	v_mul_f32_e32 v153, v69, v69
	v_fmac_f32_e32 v152, v66, v66
	v_fmac_f32_e32 v153, v68, v68
	v_add_f32_e32 v152, v152, v153
	v_add_f32_e32 v150, v150, v152
	ds_bpermute_b32 v192, v1, v150
	v_add_u32_e32 v143, 0x20000, v143
	global_load_dwordx4 v[168:171], v143, s[2:3] offset:0
	global_load_dwordx4 v[172:175], v143, s[2:3] offset:64
	global_load_dwordx4 v[176:179], v143, s[2:3] offset:512
	global_load_dwordx4 v[180:183], v143, s[2:3] offset:576
	s_waitcnt lgkmcnt(0)
	v_add_f32_e32 v150, v150, v192
	ds_bpermute_b32 v192, v142, v150
	v_add_u32_e32 v148, 0xa0000, v148
	v_add_u32_e32 v147, 0x50000, v147
	s_and_saveexec_b64 s[12:13], s[6:7]
	s_waitcnt lgkmcnt(0)
	v_add_f32_e32 v150, v150, v192
	global_atomic_add_f32 v146, v150, s[70:71] offset:192
	s_mov_b64 exec, s[12:13]
	s_waitcnt vmcnt(27)
; __device__ __forceinline__ unsigned cvt_pk_bf16(float lo, float hi) { f32x2 v = {lo, hi}; bf16x2_t b = __builtin_convertvector(v, bf16x2_t); return __builtin_bit_cast(unsigned, b); }
; template <int MODE> __device__ __forceinline__ void gemm_epilogue(f32x4 (&acc)[2][2][4][2], const GD& g, const pg8::Unit& u, int wr, int wc, int fr, int fq, LAS unsigned char* lds, const float (&rsv)[2][4]) {
;     ...
; #pragma unroll
;         for (int ai = 0; ai < 2; ++ai)
; #pragma unroll
;             for (int m = 0; m < 4; ++m) { const size_t off = (size_t)(rz + rt + ai * 128 + m * 16) * DM + col0;
;                 float ss = 0.f;
; #pragma unroll
;                 for (int bj = 0; bj < 2; ++bj)
; #pragma unroll
;                     for (int n = 0; n < 2; ++n) { const f32x4 bs = *(const f32x4*)(base + off + bj * 128 + n * 16); const f32x4 y = bs + acc[ai][bj][m][n]; *(f32x4*)(out + off + bj * 128 + n * 16) = y;
;                         ss += (y[0] * y[0] + y[1] * y[1]) + (y[2] * y[2] + y[3] * y[3]);
;                         u32x2 w; w.x = cvt_pk_bf16(y[0], y[1]); w.y = cvt_pk_bf16(y[2], y[3]); if (xb) *(u32x2*)(xb + off + bj * 128 + n * 16) = w; }
;                 ss += __shfl_xor(ss, 16); ss += __shfl_xor(ss, 32);
;                 if (fq == 0) __hip_atomic_fetch_add(ssq + rz + rt + ai * 128 + m * 16, ss, __ATOMIC_RELAXED, __HIP_MEMORY_SCOPE_AGENT); }
	v_pk_add_f32 v[64:65], v[64:65], v[186:187]
	v_pk_add_f32 v[62:63], v[62:63], v[184:185]
	v_pk_add_f32 v[60:61], v[60:61], v[190:191]
	v_pk_add_f32 v[58:59], v[58:59], v[188:189]
	v_pk_add_f32 v[56:57], v[56:57], v[198:199]
	v_pk_add_f32 v[54:55], v[54:55], v[196:197]
	v_pk_add_f32 v[52:53], v[52:53], v[206:207]
	v_pk_add_f32 v[50:51], v[50:51], v[204:205]
	global_store_dwordx4 v148, v[62:65], s[8:9] offset:0
	global_store_dwordx4 v148, v[58:61], s[8:9] offset:64
	global_store_dwordx4 v148, v[54:57], s[8:9] offset:512
	global_store_dwordx4 v148, v[50:53], s[8:9] offset:576
	v_cvt_pk_bf16_f32 v184, v62, v63
	v_cvt_pk_bf16_f32 v185, v64, v65
	v_cvt_pk_bf16_f32 v188, v58, v59
	v_cvt_pk_bf16_f32 v189, v60, v61
	v_cvt_pk_bf16_f32 v196, v54, v55
	v_cvt_pk_bf16_f32 v197, v56, v57
	v_cvt_pk_bf16_f32 v204, v50, v51
	v_cvt_pk_bf16_f32 v205, v52, v53
	global_store_dwordx2 v147, v[184:185], s[36:37] offset:0
	global_store_dwordx2 v147, v[188:189], s[36:37] offset:32
	global_store_dwordx2 v147, v[196:197], s[36:37] offset:256
	global_store_dwordx2 v147, v[204:205], s[36:37] offset:288
	v_mul_f32_e32 v150, v63, v63
	v_mul_f32_e32 v151, v65, v65
	v_fmac_f32_e32 v150, v62, v62
	v_fmac_f32_e32 v151, v64, v64
	v_add_f32_e32 v150, v150, v151
	v_mul_f32_e32 v152, v59, v59
	v_mul_f32_e32 v153, v61, v61
	v_fmac_f32_e32 v152, v58, v58
	v_fmac_f32_e32 v153, v60, v60
	v_add_f32_e32 v152, v152, v153
	v_add_f32_e32 v150, v150, v152
	v_mul_f32_e32 v152, v55, v55
	v_mul_f32_e32 v153, v57, v57
	v_fmac_f32_e32 v152, v54, v54
	v_fmac_f32_e32 v153, v56, v56
	v_add_f32_e32 v152, v152, v153
	v_add_f32_e32 v150, v150, v152
	v_mul_f32_e32 v152, v51, v51
	v_mul_f32_e32 v153, v53, v53
	v_fmac_f32_e32 v152, v50, v50
	v_fmac_f32_e32 v153, v52, v52
	v_add_f32_e32 v152, v152, v153
	v_add_f32_e32 v150, v150, v152
	ds_bpermute_b32 v192, v1, v150
	v_add_u32_e32 v143, 0x20000, v143
	global_load_dwordx4 v[184:187], v143, s[2:3] offset:0
	global_load_dwordx4 v[188:191], v143, s[2:3] offset:64
	global_load_dwordx4 v[196:199], v143, s[2:3] offset:512
	global_load_dwordx4 v[204:207], v143, s[2:3] offset:576
	s_waitcnt lgkmcnt(0)
	v_add_f32_e32 v150, v150, v192
	ds_bpermute_b32 v192, v142, v150
	v_add_u32_e32 v148, 0x20000, v148
	v_add_u32_e32 v147, 0x10000, v147
	s_and_saveexec_b64 s[12:13], s[6:7]
	s_waitcnt lgkmcnt(0)
	v_add_f32_e32 v150, v150, v192
	global_atomic_add_f32 v146, v150, s[70:71] offset:512
	s_mov_b64 exec, s[12:13]
	s_waitcnt vmcnt(27)
	v_pk_add_f32 v[48:49], v[48:49], v[222:223]
	v_pk_add_f32 v[46:47], v[46:47], v[220:221]
	v_pk_add_f32 v[44:45], v[44:45], v[226:227]
	v_pk_add_f32 v[42:43], v[42:43], v[224:225]
	v_pk_add_f32 v[40:41], v[40:41], v[230:231]
	v_pk_add_f32 v[38:39], v[38:39], v[228:229]
	v_pk_add_f32 v[36:37], v[36:37], v[234:235]
	v_pk_add_f32 v[34:35], v[34:35], v[232:233]
	global_store_dwordx4 v148, v[46:49], s[8:9] offset:0
	global_store_dwordx4 v148, v[42:45], s[8:9] offset:64
	global_store_dwordx4 v148, v[38:41], s[8:9] offset:512
	global_store_dwordx4 v148, v[34:37], s[8:9] offset:576
	v_cvt_pk_bf16_f32 v220, v46, v47
	v_cvt_pk_bf16_f32 v221, v48, v49
	v_cvt_pk_bf16_f32 v224, v42, v43
	v_cvt_pk_bf16_f32 v225, v44, v45
	v_cvt_pk_bf16_f32 v228, v38, v39
	v_cvt_pk_bf16_f32 v229, v40, v41
	v_cvt_pk_bf16_f32 v232, v34, v35
	v_cvt_pk_bf16_f32 v233, v36, v37
	global_store_dwordx2 v147, v[220:221], s[36:37] offset:0
	global_store_dwordx2 v147, v[224:225], s[36:37] offset:32
	global_store_dwordx2 v147, v[228:229], s[36:37] offset:256
	global_store_dwordx2 v147, v[232:233], s[36:37] offset:288
	v_mul_f32_e32 v150, v47, v47
	v_mul_f32_e32 v151, v49, v49
	v_fmac_f32_e32 v150, v46, v46
	v_fmac_f32_e32 v151, v48, v48
	v_add_f32_e32 v150, v150, v151
	v_mul_f32_e32 v152, v43, v43
	v_mul_f32_e32 v153, v45, v45
	v_fmac_f32_e32 v152, v42, v42
	v_fmac_f32_e32 v153, v44, v44
	v_add_f32_e32 v152, v152, v153
	v_add_f32_e32 v150, v150, v152
	v_mul_f32_e32 v152, v39, v39
	v_mul_f32_e32 v153, v41, v41
	v_fmac_f32_e32 v152, v38, v38
	v_fmac_f32_e32 v153, v40, v40
	v_add_f32_e32 v152, v152, v153
	v_add_f32_e32 v150, v150, v152
	v_mul_f32_e32 v152, v35, v35
	v_mul_f32_e32 v153, v37, v37
	v_fmac_f32_e32 v152, v34, v34
	v_fmac_f32_e32 v153, v36, v36
	v_add_f32_e32 v152, v152, v153
	v_add_f32_e32 v150, v150, v152
	ds_bpermute_b32 v192, v1, v150
	s_waitcnt lgkmcnt(0)
	v_add_f32_e32 v150, v150, v192
	ds_bpermute_b32 v192, v142, v150
	v_add_u32_e32 v148, 0x20000, v148
	v_add_u32_e32 v147, 0x10000, v147
	s_and_saveexec_b64 s[12:13], s[6:7]
	s_waitcnt lgkmcnt(0)
	v_add_f32_e32 v150, v150, v192
	global_atomic_add_f32 v146, v150, s[70:71] offset:576
	s_mov_b64 exec, s[12:13]
	s_waitcnt vmcnt(23)
	v_pk_add_f32 v[32:33], v[32:33], v[170:171]
	v_pk_add_f32 v[30:31], v[30:31], v[168:169]
	v_pk_add_f32 v[28:29], v[28:29], v[174:175]
	v_pk_add_f32 v[26:27], v[26:27], v[172:173]
	v_pk_add_f32 v[24:25], v[24:25], v[178:179]
	v_pk_add_f32 v[22:23], v[22:23], v[176:177]
	v_pk_add_f32 v[20:21], v[20:21], v[182:183]
	v_pk_add_f32 v[18:19], v[18:19], v[180:181]
	global_store_dwordx4 v148, v[30:33], s[8:9] offset:0
	global_store_dwordx4 v148, v[26:29], s[8:9] offset:64
	global_store_dwordx4 v148, v[22:25], s[8:9] offset:512
	global_store_dwordx4 v148, v[18:21], s[8:9] offset:576
	v_cvt_pk_bf16_f32 v168, v30, v31
	v_cvt_pk_bf16_f32 v169, v32, v33
	v_cvt_pk_bf16_f32 v172, v26, v27
	v_cvt_pk_bf16_f32 v173, v28, v29
	v_cvt_pk_bf16_f32 v176, v22, v23
	v_cvt_pk_bf16_f32 v177, v24, v25
	v_cvt_pk_bf16_f32 v180, v18, v19
	v_cvt_pk_bf16_f32 v181, v20, v21
	global_store_dwordx2 v147, v[168:169], s[36:37] offset:0
	global_store_dwordx2 v147, v[172:173], s[36:37] offset:32
	global_store_dwordx2 v147, v[176:177], s[36:37] offset:256
	global_store_dwordx2 v147, v[180:181], s[36:37] offset:288
	v_mul_f32_e32 v150, v31, v31
	v_mul_f32_e32 v151, v33, v33
	v_fmac_f32_e32 v150, v30, v30
	v_fmac_f32_e32 v151, v32, v32
	v_add_f32_e32 v150, v150, v151
	v_mul_f32_e32 v152, v27, v27
	v_mul_f32_e32 v153, v29, v29
	v_fmac_f32_e32 v152, v26, v26
	v_fmac_f32_e32 v153, v28, v28
	v_add_f32_e32 v152, v152, v153
	v_add_f32_e32 v150, v150, v152
	v_mul_f32_e32 v152, v23, v23
	v_mul_f32_e32 v153, v25, v25
	v_fmac_f32_e32 v152, v22, v22
	v_fmac_f32_e32 v153, v24, v24
	v_add_f32_e32 v152, v152, v153
	v_add_f32_e32 v150, v150, v152
	v_mul_f32_e32 v152, v19, v19
	v_mul_f32_e32 v153, v21, v21
	v_fmac_f32_e32 v152, v18, v18
	v_fmac_f32_e32 v153, v20, v20
	v_add_f32_e32 v152, v152, v153
	v_add_f32_e32 v150, v150, v152
	ds_bpermute_b32 v192, v1, v150
	s_waitcnt lgkmcnt(0)
; __device__ __forceinline__ unsigned cvt_pk_bf16(float lo, float hi) { f32x2 v = {lo, hi}; bf16x2_t b = __builtin_convertvector(v, bf16x2_t); return __builtin_bit_cast(unsigned, b); }
; template <int MODE> __device__ __forceinline__ void gemm_epilogue(f32x4 (&acc)[2][2][4][2], const GD& g, const pg8::Unit& u, int wr, int wc, int fr, int fq, LAS unsigned char* lds, const float (&rsv)[2][4]) {
;     ...
; #pragma unroll
;         for (int ai = 0; ai < 2; ++ai)
; #pragma unroll
;             for (int m = 0; m < 4; ++m) { const size_t off = (size_t)(rz + rt + ai * 128 + m * 16) * DM + col0;
;                 float ss = 0.f;
; #pragma unroll
;                 for (int bj = 0; bj < 2; ++bj)
; #pragma unroll
;                     for (int n = 0; n < 2; ++n) { const f32x4 bs = *(const f32x4*)(base + off + bj * 128 + n * 16); const f32x4 y = bs + acc[ai][bj][m][n]; *(f32x4*)(out + off + bj * 128 + n * 16) = y;
;                         ss += (y[0] * y[0] + y[1] * y[1]) + (y[2] * y[2] + y[3] * y[3]);
;                         u32x2 w; w.x = cvt_pk_bf16(y[0], y[1]); w.y = cvt_pk_bf16(y[2], y[3]); if (xb) *(u32x2*)(xb + off + bj * 128 + n * 16) = w; }
;                 ss += __shfl_xor(ss, 16); ss += __shfl_xor(ss, 32);
;                 if (fq == 0) __hip_atomic_fetch_add(ssq + rz + rt + ai * 128 + m * 16, ss, __ATOMIC_RELAXED, __HIP_MEMORY_SCOPE_AGENT); }
	v_add_f32_e32 v150, v150, v192
	ds_bpermute_b32 v192, v142, v150
	v_add_u32_e32 v148, 0x20000, v148
	v_add_u32_e32 v147, 0x10000, v147
	s_and_saveexec_b64 s[12:13], s[6:7]
	s_waitcnt lgkmcnt(0)
	v_add_f32_e32 v150, v150, v192
	global_atomic_add_f32 v146, v150, s[70:71] offset:640
	s_mov_b64 exec, s[12:13]
	s_waitcnt vmcnt(19)
	v_pk_add_f32 v[16:17], v[16:17], v[186:187]
	v_pk_add_f32 v[14:15], v[14:15], v[184:185]
	v_pk_add_f32 v[12:13], v[12:13], v[190:191]
	v_pk_add_f32 v[10:11], v[10:11], v[188:189]
	v_pk_add_f32 v[8:9], v[8:9], v[198:199]
	v_pk_add_f32 v[6:7], v[6:7], v[196:197]
	v_pk_add_f32 v[4:5], v[4:5], v[206:207]
	v_pk_add_f32 v[2:3], v[2:3], v[204:205]
	global_store_dwordx4 v148, v[14:17], s[8:9] offset:0
	global_store_dwordx4 v148, v[10:13], s[8:9] offset:64
	global_store_dwordx4 v148, v[6:9], s[8:9] offset:512
	global_store_dwordx4 v148, v[2:5], s[8:9] offset:576
	v_cvt_pk_bf16_f32 v184, v14, v15
	v_cvt_pk_bf16_f32 v185, v16, v17
	v_cvt_pk_bf16_f32 v188, v10, v11
	v_cvt_pk_bf16_f32 v189, v12, v13
	v_cvt_pk_bf16_f32 v196, v6, v7
	v_cvt_pk_bf16_f32 v197, v8, v9
	v_cvt_pk_bf16_f32 v204, v2, v3
	v_cvt_pk_bf16_f32 v205, v4, v5
	global_store_dwordx2 v147, v[184:185], s[36:37] offset:0
	global_store_dwordx2 v147, v[188:189], s[36:37] offset:32
	global_store_dwordx2 v147, v[196:197], s[36:37] offset:256
	global_store_dwordx2 v147, v[204:205], s[36:37] offset:288
	v_mul_f32_e32 v150, v15, v15
	v_mul_f32_e32 v151, v17, v17
	v_fmac_f32_e32 v150, v14, v14
	v_fmac_f32_e32 v151, v16, v16
	v_add_f32_e32 v150, v150, v151
	v_mul_f32_e32 v152, v11, v11
	v_mul_f32_e32 v153, v13, v13
	v_fmac_f32_e32 v152, v10, v10
	v_fmac_f32_e32 v153, v12, v12
	v_add_f32_e32 v152, v152, v153
	v_add_f32_e32 v150, v150, v152
	v_mul_f32_e32 v152, v7, v7
	v_mul_f32_e32 v153, v9, v9
	v_fmac_f32_e32 v152, v6, v6
	v_fmac_f32_e32 v153, v8, v8
	v_add_f32_e32 v152, v152, v153
	v_add_f32_e32 v150, v150, v152
	v_mul_f32_e32 v152, v3, v3
	v_mul_f32_e32 v153, v5, v5
	v_fmac_f32_e32 v152, v2, v2
	v_fmac_f32_e32 v153, v4, v4
	v_add_f32_e32 v152, v152, v153
	v_add_f32_e32 v150, v150, v152
	ds_bpermute_b32 v192, v1, v150
	s_waitcnt lgkmcnt(0)
	v_add_f32_e32 v150, v150, v192
	ds_bpermute_b32 v192, v142, v150
	s_and_saveexec_b64 s[12:13], s[6:7]
	s_waitcnt lgkmcnt(0)
	v_add_f32_e32 v150, v150, v192
	global_atomic_add_f32 v146, v150, s[70:71] offset:704
	s_mov_b64 exec, s[12:13]
	s_branch .Lres_done
.Lres_noxb:
	global_load_dwordx4 v[168:171], v143, s[2:3] offset:0
	global_load_dwordx4 v[172:175], v143, s[2:3] offset:64
	global_load_dwordx4 v[176:179], v143, s[2:3] offset:512
	global_load_dwordx4 v[180:183], v143, s[2:3] offset:576
	v_add_u32_e32 v143, 0x20000, v143
	global_load_dwordx4 v[184:187], v143, s[2:3] offset:0
	global_load_dwordx4 v[188:191], v143, s[2:3] offset:64
	global_load_dwordx4 v[196:199], v143, s[2:3] offset:512
	global_load_dwordx4 v[204:207], v143, s[2:3] offset:576
	v_add_u32_e32 v143, 0x20000, v143
	global_load_dwordx4 v[220:223], v143, s[2:3] offset:0
	global_load_dwordx4 v[224:227], v143, s[2:3] offset:64
	global_load_dwordx4 v[228:231], v143, s[2:3] offset:512
	global_load_dwordx4 v[232:235], v143, s[2:3] offset:576
	s_waitcnt vmcnt(8)
	v_pk_add_f32 v[128:129], v[128:129], v[170:171]
	v_pk_add_f32 v[126:127], v[126:127], v[168:169]
	v_pk_add_f32 v[124:125], v[124:125], v[174:175]
	v_pk_add_f32 v[122:123], v[122:123], v[172:173]
	v_pk_add_f32 v[120:121], v[120:121], v[178:179]
	v_pk_add_f32 v[118:119], v[118:119], v[176:177]
	v_pk_add_f32 v[116:117], v[116:117], v[182:183]
	v_pk_add_f32 v[114:115], v[114:115], v[180:181]
	global_store_dwordx4 v148, v[126:129], s[8:9] offset:0
	global_store_dwordx4 v148, v[122:125], s[8:9] offset:64
	global_store_dwordx4 v148, v[118:121], s[8:9] offset:512
	global_store_dwordx4 v148, v[114:117], s[8:9] offset:576
	v_mul_f32_e32 v150, v127, v127
	v_mul_f32_e32 v151, v129, v129
	v_fmac_f32_e32 v150, v126, v126
	v_fmac_f32_e32 v151, v128, v128
	v_add_f32_e32 v150, v150, v151
	v_mul_f32_e32 v152, v123, v123
	v_mul_f32_e32 v153, v125, v125
	v_fmac_f32_e32 v152, v122, v122
	v_fmac_f32_e32 v153, v124, v124
	v_add_f32_e32 v152, v152, v153
	v_add_f32_e32 v150, v150, v152
	v_mul_f32_e32 v152, v119, v119
	v_mul_f32_e32 v153, v121, v121
	v_fmac_f32_e32 v152, v118, v118
	v_fmac_f32_e32 v153, v120, v120
	v_add_f32_e32 v152, v152, v153
	v_add_f32_e32 v150, v150, v152
	v_mul_f32_e32 v152, v115, v115
	v_mul_f32_e32 v153, v117, v117
	v_fmac_f32_e32 v152, v114, v114
	v_fmac_f32_e32 v153, v116, v116
	v_add_f32_e32 v152, v152, v153
	v_add_f32_e32 v150, v150, v152
	ds_bpermute_b32 v192, v1, v150
	v_add_u32_e32 v143, 0x20000, v143
	global_load_dwordx4 v[168:171], v143, s[2:3] offset:0
	global_load_dwordx4 v[172:175], v143, s[2:3] offset:64
	global_load_dwordx4 v[176:179], v143, s[2:3] offset:512
	global_load_dwordx4 v[180:183], v143, s[2:3] offset:576
	s_waitcnt lgkmcnt(0)
	v_add_f32_e32 v150, v150, v192
	ds_bpermute_b32 v192, v142, v150
	v_add_u32_e32 v148, 0x20000, v148
	s_and_saveexec_b64 s[12:13], s[6:7]
	s_waitcnt lgkmcnt(0)
	v_add_f32_e32 v150, v150, v192
	global_atomic_add_f32 v146, v150, s[70:71] offset:0
	s_mov_b64 exec, s[12:13]
	s_waitcnt vmcnt(13)
; __device__ __forceinline__ unsigned cvt_pk_bf16(float lo, float hi) { f32x2 v = {lo, hi}; bf16x2_t b = __builtin_convertvector(v, bf16x2_t); return __builtin_bit_cast(unsigned, b); }
; template <int MODE> __device__ __forceinline__ void gemm_epilogue(f32x4 (&acc)[2][2][4][2], const GD& g, const pg8::Unit& u, int wr, int wc, int fr, int fq, LAS unsigned char* lds, const float (&rsv)[2][4]) {
;     ...
; #pragma unroll
;         for (int ai = 0; ai < 2; ++ai)
; #pragma unroll
;             for (int m = 0; m < 4; ++m) { const size_t off = (size_t)(rz + rt + ai * 128 + m * 16) * DM + col0;
;                 float ss = 0.f;
; #pragma unroll
;                 for (int bj = 0; bj < 2; ++bj)
; #pragma unroll
;                     for (int n = 0; n < 2; ++n) { const f32x4 bs = *(const f32x4*)(base + off + bj * 128 + n * 16); const f32x4 y = bs + acc[ai][bj][m][n]; *(f32x4*)(out + off + bj * 128 + n * 16) = y;
;                         ss += (y[0] * y[0] + y[1] * y[1]) + (y[2] * y[2] + y[3] * y[3]);
;                         u32x2 w; w.x = cvt_pk_bf16(y[0], y[1]); w.y = cvt_pk_bf16(y[2], y[3]); if (xb) *(u32x2*)(xb + off + bj * 128 + n * 16) = w; }
;                 ss += __shfl_xor(ss, 16); ss += __shfl_xor(ss, 32);
;                 if (fq == 0) __hip_atomic_fetch_add(ssq + rz + rt + ai * 128 + m * 16, ss, __ATOMIC_RELAXED, __HIP_MEMORY_SCOPE_AGENT); }
	v_pk_add_f32 v[112:113], v[112:113], v[186:187]
	v_pk_add_f32 v[110:111], v[110:111], v[184:185]
	v_pk_add_f32 v[108:109], v[108:109], v[190:191]
	v_pk_add_f32 v[106:107], v[106:107], v[188:189]
	v_pk_add_f32 v[104:105], v[104:105], v[198:199]
	v_pk_add_f32 v[102:103], v[102:103], v[196:197]
	v_pk_add_f32 v[100:101], v[100:101], v[206:207]
	v_pk_add_f32 v[98:99], v[98:99], v[204:205]
	global_store_dwordx4 v148, v[110:113], s[8:9] offset:0
	global_store_dwordx4 v148, v[106:109], s[8:9] offset:64
	global_store_dwordx4 v148, v[102:105], s[8:9] offset:512
	global_store_dwordx4 v148, v[98:101], s[8:9] offset:576
	v_mul_f32_e32 v150, v111, v111
	v_mul_f32_e32 v151, v113, v113
	v_fmac_f32_e32 v150, v110, v110
	v_fmac_f32_e32 v151, v112, v112
	v_add_f32_e32 v150, v150, v151
	v_mul_f32_e32 v152, v107, v107
	v_mul_f32_e32 v153, v109, v109
	v_fmac_f32_e32 v152, v106, v106
	v_fmac_f32_e32 v153, v108, v108
	v_add_f32_e32 v152, v152, v153
	v_add_f32_e32 v150, v150, v152
	v_mul_f32_e32 v152, v103, v103
	v_mul_f32_e32 v153, v105, v105
	v_fmac_f32_e32 v152, v102, v102
	v_fmac_f32_e32 v153, v104, v104
	v_add_f32_e32 v152, v152, v153
	v_add_f32_e32 v150, v150, v152
	v_mul_f32_e32 v152, v99, v99
	v_mul_f32_e32 v153, v101, v101
	v_fmac_f32_e32 v152, v98, v98
	v_fmac_f32_e32 v153, v100, v100
	v_add_f32_e32 v152, v152, v153
	v_add_f32_e32 v150, v150, v152
	ds_bpermute_b32 v192, v1, v150
	v_add_u32_e32 v143, 0xa0000, v143
	global_load_dwordx4 v[184:187], v143, s[2:3] offset:0
	global_load_dwordx4 v[188:191], v143, s[2:3] offset:64
	global_load_dwordx4 v[196:199], v143, s[2:3] offset:512
	global_load_dwordx4 v[204:207], v143, s[2:3] offset:576
	s_waitcnt lgkmcnt(0)
	v_add_f32_e32 v150, v150, v192
	ds_bpermute_b32 v192, v142, v150
	v_add_u32_e32 v148, 0x20000, v148
	s_and_saveexec_b64 s[12:13], s[6:7]
	s_waitcnt lgkmcnt(0)
	v_add_f32_e32 v150, v150, v192
	global_atomic_add_f32 v146, v150, s[70:71] offset:64
	s_mov_b64 exec, s[12:13]
	s_waitcnt vmcnt(18)
	v_pk_add_f32 v[96:97], v[96:97], v[222:223]
	v_pk_add_f32 v[94:95], v[94:95], v[220:221]
	v_pk_add_f32 v[92:93], v[92:93], v[226:227]
	v_pk_add_f32 v[90:91], v[90:91], v[224:225]
	v_pk_add_f32 v[88:89], v[88:89], v[230:231]
	v_pk_add_f32 v[86:87], v[86:87], v[228:229]
	v_pk_add_f32 v[84:85], v[84:85], v[234:235]
	v_pk_add_f32 v[82:83], v[82:83], v[232:233]
	global_store_dwordx4 v148, v[94:97], s[8:9] offset:0
	global_store_dwordx4 v148, v[90:93], s[8:9] offset:64
	global_store_dwordx4 v148, v[86:89], s[8:9] offset:512
	global_store_dwordx4 v148, v[82:85], s[8:9] offset:576
	v_mul_f32_e32 v150, v95, v95
	v_mul_f32_e32 v151, v97, v97
	v_fmac_f32_e32 v150, v94, v94
	v_fmac_f32_e32 v151, v96, v96
	v_add_f32_e32 v150, v150, v151
	v_mul_f32_e32 v152, v91, v91
	v_mul_f32_e32 v153, v93, v93
	v_fmac_f32_e32 v152, v90, v90
	v_fmac_f32_e32 v153, v92, v92
	v_add_f32_e32 v152, v152, v153
	v_add_f32_e32 v150, v150, v152
	v_mul_f32_e32 v152, v87, v87
	v_mul_f32_e32 v153, v89, v89
	v_fmac_f32_e32 v152, v86, v86
	v_fmac_f32_e32 v153, v88, v88
	v_add_f32_e32 v152, v152, v153
	v_add_f32_e32 v150, v150, v152
	v_mul_f32_e32 v152, v83, v83
	v_mul_f32_e32 v153, v85, v85
	v_fmac_f32_e32 v152, v82, v82
	v_fmac_f32_e32 v153, v84, v84
	v_add_f32_e32 v152, v152, v153
	v_add_f32_e32 v150, v150, v152
	ds_bpermute_b32 v192, v1, v150
	v_add_u32_e32 v143, 0x20000, v143
	global_load_dwordx4 v[220:223], v143, s[2:3] offset:0
	global_load_dwordx4 v[224:227], v143, s[2:3] offset:64
	global_load_dwordx4 v[228:231], v143, s[2:3] offset:512
	global_load_dwordx4 v[232:235], v143, s[2:3] offset:576
	s_waitcnt lgkmcnt(0)
	v_add_f32_e32 v150, v150, v192
	ds_bpermute_b32 v192, v142, v150
	v_add_u32_e32 v148, 0x20000, v148
	s_and_saveexec_b64 s[12:13], s[6:7]
	s_waitcnt lgkmcnt(0)
	v_add_f32_e32 v150, v150, v192
	global_atomic_add_f32 v146, v150, s[70:71] offset:128
	s_mov_b64 exec, s[12:13]
	s_waitcnt vmcnt(19)
	v_pk_add_f32 v[80:81], v[80:81], v[170:171]
	v_pk_add_f32 v[78:79], v[78:79], v[168:169]
	v_pk_add_f32 v[76:77], v[76:77], v[174:175]
	v_pk_add_f32 v[74:75], v[74:75], v[172:173]
	v_pk_add_f32 v[72:73], v[72:73], v[178:179]
	v_pk_add_f32 v[70:71], v[70:71], v[176:177]
	v_pk_add_f32 v[68:69], v[68:69], v[182:183]
	v_pk_add_f32 v[66:67], v[66:67], v[180:181]
	global_store_dwordx4 v148, v[78:81], s[8:9] offset:0
	global_store_dwordx4 v148, v[74:77], s[8:9] offset:64
	global_store_dwordx4 v148, v[70:73], s[8:9] offset:512
	global_store_dwordx4 v148, v[66:69], s[8:9] offset:576
	v_mul_f32_e32 v150, v79, v79
	v_mul_f32_e32 v151, v81, v81
	v_fmac_f32_e32 v150, v78, v78
	v_fmac_f32_e32 v151, v80, v80
	v_add_f32_e32 v150, v150, v151
	v_mul_f32_e32 v152, v75, v75
	v_mul_f32_e32 v153, v77, v77
	v_fmac_f32_e32 v152, v74, v74
	v_fmac_f32_e32 v153, v76, v76
	v_add_f32_e32 v152, v152, v153
	v_add_f32_e32 v150, v150, v152
	v_mul_f32_e32 v152, v71, v71
	v_mul_f32_e32 v153, v73, v73
	v_fmac_f32_e32 v152, v70, v70
	v_fmac_f32_e32 v153, v72, v72
	v_add_f32_e32 v152, v152, v153
	v_add_f32_e32 v150, v150, v152
	v_mul_f32_e32 v152, v67, v67
	v_mul_f32_e32 v153, v69, v69
	v_fmac_f32_e32 v152, v66, v66
	v_fmac_f32_e32 v153, v68, v68
	v_add_f32_e32 v152, v152, v153
	v_add_f32_e32 v150, v150, v152
	ds_bpermute_b32 v192, v1, v150
	v_add_u32_e32 v143, 0x20000, v143
	global_load_dwordx4 v[168:171], v143, s[2:3] offset:0
	global_load_dwordx4 v[172:175], v143, s[2:3] offset:64
	global_load_dwordx4 v[176:179], v143, s[2:3] offset:512
	global_load_dwordx4 v[180:183], v143, s[2:3] offset:576
	s_waitcnt lgkmcnt(0)
	v_add_f32_e32 v150, v150, v192
	ds_bpermute_b32 v192, v142, v150
	v_add_u32_e32 v148, 0xa0000, v148
	s_and_saveexec_b64 s[12:13], s[6:7]
	s_waitcnt lgkmcnt(0)
; __device__ __forceinline__ unsigned cvt_pk_bf16(float lo, float hi) { f32x2 v = {lo, hi}; bf16x2_t b = __builtin_convertvector(v, bf16x2_t); return __builtin_bit_cast(unsigned, b); }
; template <int MODE> __device__ __forceinline__ void gemm_epilogue(f32x4 (&acc)[2][2][4][2], const GD& g, const pg8::Unit& u, int wr, int wc, int fr, int fq, LAS unsigned char* lds, const float (&rsv)[2][4]) {
;     ...
; #pragma unroll
;         for (int ai = 0; ai < 2; ++ai)
; #pragma unroll
;             for (int m = 0; m < 4; ++m) { const size_t off = (size_t)(rz + rt + ai * 128 + m * 16) * DM + col0;
;                 float ss = 0.f;
; #pragma unroll
;                 for (int bj = 0; bj < 2; ++bj)
; #pragma unroll
;                     for (int n = 0; n < 2; ++n) { const f32x4 bs = *(const f32x4*)(base + off + bj * 128 + n * 16); const f32x4 y = bs + acc[ai][bj][m][n]; *(f32x4*)(out + off + bj * 128 + n * 16) = y;
;                         ss += (y[0] * y[0] + y[1] * y[1]) + (y[2] * y[2] + y[3] * y[3]);
;                         u32x2 w; w.x = cvt_pk_bf16(y[0], y[1]); w.y = cvt_pk_bf16(y[2], y[3]); if (xb) *(u32x2*)(xb + off + bj * 128 + n * 16) = w; }
;                 ss += __shfl_xor(ss, 16); ss += __shfl_xor(ss, 32);
;                 if (fq == 0) __hip_atomic_fetch_add(ssq + rz + rt + ai * 128 + m * 16, ss, __ATOMIC_RELAXED, __HIP_MEMORY_SCOPE_AGENT); }
	v_add_f32_e32 v150, v150, v192
	global_atomic_add_f32 v146, v150, s[70:71] offset:192
	s_mov_b64 exec, s[12:13]
	s_waitcnt vmcnt(19)
	v_pk_add_f32 v[64:65], v[64:65], v[186:187]
	v_pk_add_f32 v[62:63], v[62:63], v[184:185]
	v_pk_add_f32 v[60:61], v[60:61], v[190:191]
	v_pk_add_f32 v[58:59], v[58:59], v[188:189]
	v_pk_add_f32 v[56:57], v[56:57], v[198:199]
	v_pk_add_f32 v[54:55], v[54:55], v[196:197]
	v_pk_add_f32 v[52:53], v[52:53], v[206:207]
	v_pk_add_f32 v[50:51], v[50:51], v[204:205]
	global_store_dwordx4 v148, v[62:65], s[8:9] offset:0
	global_store_dwordx4 v148, v[58:61], s[8:9] offset:64
	global_store_dwordx4 v148, v[54:57], s[8:9] offset:512
	global_store_dwordx4 v148, v[50:53], s[8:9] offset:576
	v_mul_f32_e32 v150, v63, v63
	v_mul_f32_e32 v151, v65, v65
	v_fmac_f32_e32 v150, v62, v62
	v_fmac_f32_e32 v151, v64, v64
	v_add_f32_e32 v150, v150, v151
	v_mul_f32_e32 v152, v59, v59
	v_mul_f32_e32 v153, v61, v61
	v_fmac_f32_e32 v152, v58, v58
	v_fmac_f32_e32 v153, v60, v60
	v_add_f32_e32 v152, v152, v153
	v_add_f32_e32 v150, v150, v152
	v_mul_f32_e32 v152, v55, v55
	v_mul_f32_e32 v153, v57, v57
	v_fmac_f32_e32 v152, v54, v54
	v_fmac_f32_e32 v153, v56, v56
	v_add_f32_e32 v152, v152, v153
	v_add_f32_e32 v150, v150, v152
	v_mul_f32_e32 v152, v51, v51
	v_mul_f32_e32 v153, v53, v53
	v_fmac_f32_e32 v152, v50, v50
	v_fmac_f32_e32 v153, v52, v52
	v_add_f32_e32 v152, v152, v153
	v_add_f32_e32 v150, v150, v152
	ds_bpermute_b32 v192, v1, v150
	v_add_u32_e32 v143, 0x20000, v143
	global_load_dwordx4 v[184:187], v143, s[2:3] offset:0
	global_load_dwordx4 v[188:191], v143, s[2:3] offset:64
	global_load_dwordx4 v[196:199], v143, s[2:3] offset:512
	global_load_dwordx4 v[204:207], v143, s[2:3] offset:576
	s_waitcnt lgkmcnt(0)
	v_add_f32_e32 v150, v150, v192
	ds_bpermute_b32 v192, v142, v150
	v_add_u32_e32 v148, 0x20000, v148
	s_and_saveexec_b64 s[12:13], s[6:7]
	s_waitcnt lgkmcnt(0)
	v_add_f32_e32 v150, v150, v192
	global_atomic_add_f32 v146, v150, s[70:71] offset:512
	s_mov_b64 exec, s[12:13]
	s_waitcnt vmcnt(19)
	v_pk_add_f32 v[48:49], v[48:49], v[222:223]
	v_pk_add_f32 v[46:47], v[46:47], v[220:221]
	v_pk_add_f32 v[44:45], v[44:45], v[226:227]
	v_pk_add_f32 v[42:43], v[42:43], v[224:225]
	v_pk_add_f32 v[40:41], v[40:41], v[230:231]
	v_pk_add_f32 v[38:39], v[38:39], v[228:229]
	v_pk_add_f32 v[36:37], v[36:37], v[234:235]
	v_pk_add_f32 v[34:35], v[34:35], v[232:233]
	global_store_dwordx4 v148, v[46:49], s[8:9] offset:0
	global_store_dwordx4 v148, v[42:45], s[8:9] offset:64
	global_store_dwordx4 v148, v[38:41], s[8:9] offset:512
	global_store_dwordx4 v148, v[34:37], s[8:9] offset:576
	v_mul_f32_e32 v150, v47, v47
	v_mul_f32_e32 v151, v49, v49
	v_fmac_f32_e32 v150, v46, v46
	v_fmac_f32_e32 v151, v48, v48
	v_add_f32_e32 v150, v150, v151
	v_mul_f32_e32 v152, v43, v43
	v_mul_f32_e32 v153, v45, v45
	v_fmac_f32_e32 v152, v42, v42
	v_fmac_f32_e32 v153, v44, v44
	v_add_f32_e32 v152, v152, v153
	v_add_f32_e32 v150, v150, v152
	v_mul_f32_e32 v152, v39, v39
	v_mul_f32_e32 v153, v41, v41
	v_fmac_f32_e32 v152, v38, v38
	v_fmac_f32_e32 v153, v40, v40
	v_add_f32_e32 v152, v152, v153
	v_add_f32_e32 v150, v150, v152
	v_mul_f32_e32 v152, v35, v35
	v_mul_f32_e32 v153, v37, v37
	v_fmac_f32_e32 v152, v34, v34
	v_fmac_f32_e32 v153, v36, v36
	v_add_f32_e32 v152, v152, v153
	v_add_f32_e32 v150, v150, v152
	ds_bpermute_b32 v192, v1, v150
	s_waitcnt lgkmcnt(0)
	v_add_f32_e32 v150, v150, v192
	ds_bpermute_b32 v192, v142, v150
	v_add_u32_e32 v148, 0x20000, v148
	s_and_saveexec_b64 s[12:13], s[6:7]
	s_waitcnt lgkmcnt(0)
	v_add_f32_e32 v150, v150, v192
	global_atomic_add_f32 v146, v150, s[70:71] offset:576
	s_mov_b64 exec, s[12:13]
	s_waitcnt vmcnt(15)
	v_pk_add_f32 v[32:33], v[32:33], v[170:171]
	v_pk_add_f32 v[30:31], v[30:31], v[168:169]
	v_pk_add_f32 v[28:29], v[28:29], v[174:175]
	v_pk_add_f32 v[26:27], v[26:27], v[172:173]
	v_pk_add_f32 v[24:25], v[24:25], v[178:179]
	v_pk_add_f32 v[22:23], v[22:23], v[176:177]
	v_pk_add_f32 v[20:21], v[20:21], v[182:183]
	v_pk_add_f32 v[18:19], v[18:19], v[180:181]
	global_store_dwordx4 v148, v[30:33], s[8:9] offset:0
	global_store_dwordx4 v148, v[26:29], s[8:9] offset:64
	global_store_dwordx4 v148, v[22:25], s[8:9] offset:512
	global_store_dwordx4 v148, v[18:21], s[8:9] offset:576
	v_mul_f32_e32 v150, v31, v31
	v_mul_f32_e32 v151, v33, v33
	v_fmac_f32_e32 v150, v30, v30
	v_fmac_f32_e32 v151, v32, v32
	v_add_f32_e32 v150, v150, v151
	v_mul_f32_e32 v152, v27, v27
	v_mul_f32_e32 v153, v29, v29
	v_fmac_f32_e32 v152, v26, v26
	v_fmac_f32_e32 v153, v28, v28
	v_add_f32_e32 v152, v152, v153
	v_add_f32_e32 v150, v150, v152
	v_mul_f32_e32 v152, v23, v23
	v_mul_f32_e32 v153, v25, v25
	v_fmac_f32_e32 v152, v22, v22
	v_fmac_f32_e32 v153, v24, v24
	v_add_f32_e32 v152, v152, v153
	v_add_f32_e32 v150, v150, v152
	v_mul_f32_e32 v152, v19, v19
	v_mul_f32_e32 v153, v21, v21
	v_fmac_f32_e32 v152, v18, v18
	v_fmac_f32_e32 v153, v20, v20
	v_add_f32_e32 v152, v152, v153
	v_add_f32_e32 v150, v150, v152
	ds_bpermute_b32 v192, v1, v150
	s_waitcnt lgkmcnt(0)
	v_add_f32_e32 v150, v150, v192
	ds_bpermute_b32 v192, v142, v150
	v_add_u32_e32 v148, 0x20000, v148
	s_and_saveexec_b64 s[12:13], s[6:7]
	s_waitcnt lgkmcnt(0)
	v_add_f32_e32 v150, v150, v192
	global_atomic_add_f32 v146, v150, s[70:71] offset:640
	s_mov_b64 exec, s[12:13]
	s_waitcnt vmcnt(11)
	v_pk_add_f32 v[16:17], v[16:17], v[186:187]
	v_pk_add_f32 v[14:15], v[14:15], v[184:185]
	v_pk_add_f32 v[12:13], v[12:13], v[190:191]
	v_pk_add_f32 v[10:11], v[10:11], v[188:189]
	v_pk_add_f32 v[8:9], v[8:9], v[198:199]
	v_pk_add_f32 v[6:7], v[6:7], v[196:197]
	v_pk_add_f32 v[4:5], v[4:5], v[206:207]
	v_pk_add_f32 v[2:3], v[2:3], v[204:205]
	global_store_dwordx4 v148, v[14:17], s[8:9] offset:0
	global_store_dwordx4 v148, v[10:13], s[8:9] offset:64
	global_store_dwordx4 v148, v[6:9], s[8:9] offset:512
	global_store_dwordx4 v148, v[2:5], s[8:9] offset:576
	v_mul_f32_e32 v150, v15, v15
	v_mul_f32_e32 v151, v17, v17
	v_fmac_f32_e32 v150, v14, v14
	v_fmac_f32_e32 v151, v16, v16
	v_add_f32_e32 v150, v150, v151
	v_mul_f32_e32 v152, v11, v11
	v_mul_f32_e32 v153, v13, v13
	v_fmac_f32_e32 v152, v10, v10
	v_fmac_f32_e32 v153, v12, v12
	v_add_f32_e32 v152, v152, v153
	v_add_f32_e32 v150, v150, v152
	v_mul_f32_e32 v152, v7, v7
	v_mul_f32_e32 v153, v9, v9
	v_fmac_f32_e32 v152, v6, v6
	v_fmac_f32_e32 v153, v8, v8
	v_add_f32_e32 v152, v152, v153
	v_add_f32_e32 v150, v150, v152
	v_mul_f32_e32 v152, v3, v3
	v_mul_f32_e32 v153, v5, v5
	v_fmac_f32_e32 v152, v2, v2
	v_fmac_f32_e32 v153, v4, v4
	v_add_f32_e32 v152, v152, v153
	v_add_f32_e32 v150, v150, v152
	ds_bpermute_b32 v192, v1, v150
	s_waitcnt lgkmcnt(0)
	v_add_f32_e32 v150, v150, v192
	ds_bpermute_b32 v192, v142, v150
	s_and_saveexec_b64 s[12:13], s[6:7]
	s_waitcnt lgkmcnt(0)
	v_add_f32_e32 v150, v150, v192
	global_atomic_add_f32 v146, v150, s[70:71] offset:704
	s_mov_b64 exec, s[12:13]
; __device__ __forceinline__ void rsv_load(float (&rsv)[2][4], const GD& g, const pg8::Unit& u, int wr, int fr) {
;     if (g.f2) { const int rg = (u.z / g.nz2) * g.ro1 + u.pm * 256 + wr * 64 + fr;
; #pragma unroll
;         for (int ai = 0; ai < 2; ++ai)
; #pragma unroll
;             for (int m = 0; m < 4; ++m) rsv[ai][m] = g.f2[rg + ai * 128 + m * 16]; }
.Lres_done:
	s_andn2_b64 vcc, exec, s[92:93]
	s_mov_b64 s[2:3], -1
	s_cbranch_vccnz .LBB0_168
	s_and_b64 vcc, exec, s[44:45]
	s_cbranch_vccz .LBB0_167
	s_abs_i32 s3, s14
	s_mul_hi_u32 s8, s3, s0
	s_mul_i32 s9, s8, s1
	s_ashr_i32 s2, s14, 31
	s_sub_i32 s3, s3, s9
	s_xor_b32 s2, s2, s52
	s_add_i32 s9, s8, 1
	s_sub_i32 s12, s3, s1
	s_cmp_ge_u32 s3, s1
	s_cselect_b32 s8, s9, s8
	s_cselect_b32 s3, s12, s3
	s_add_i32 s9, s8, 1
	s_cmp_ge_u32 s3, s1
	s_cselect_b32 s3, s9, s8
	s_xor_b32 s3, s3, s2
	s_sub_i32 s2, s3, s2
	v_readlane_b32 s3, v254, 59
	s_mul_i32 s2, s2, s3
	s_lshl_b32 s3, s15, 8
	s_add_i32 s2, s2, s3
	s_waitcnt lgkmcnt(0)
	v_add_u32_e32 v2, s2, v154
	v_readlane_b32 s2, v254, 52
	v_ashrrev_i32_e32 v3, 31, v2
	v_readlane_b32 s3, v254, 53
	s_nop 1
	v_lshl_add_u64 v[2:3], v[2:3], 2, s[2:3]
	flat_load_dword v155, v[2:3]
	flat_load_dword v156, v[2:3] offset:64
	flat_load_dword v157, v[2:3] offset:128
	flat_load_dword v158, v[2:3] offset:192
	flat_load_dword v159, v[2:3] offset:512
	flat_load_dword v160, v[2:3] offset:576
	flat_load_dword v161, v[2:3] offset:640
	flat_load_dword v162, v[2:3] offset:704
	s_branch .LBB0_167
